# v_ntwin + peeled first K iteration (SrcC=0, no accumulator zeroing) + in-proj rstd loads issued before the K-loop
# speedup vs baseline: 1.0197x; 1.0023x over previous
; #define PG8_STAGE(bufoff, gbase, voff) do { _Pragma("unroll") for (int _i = 0; _i < 2; ++_i) \
;         __builtin_amdgcn_global_load_lds((const unsigned*)((const char*)(gbase) + (voff)[_i]), (PG8_LAS unsigned*)(lds + (bufoff) + ldsw + _i * 8192), 16, 0, 0); } while (0)
; #define PG8_LDA(dst, b, h) do { _Pragma("unroll") for (int m = 0; m < 4; ++m) _Pragma("unroll") for (int k = 0; k < 2; ++k) dst[m][k] = *(const PG8_LAS bf16x8*)(lds + PG8_SA(b, h) + aoff + m * 2048 + k * 1024); } while (0)
; #define PG8_LDB(dst, b, h) do { _Pragma("unroll") for (int n = 0; n < 2; ++n) _Pragma("unroll") for (int k = 0; k < 2; ++k) dst[n][k] = *(const PG8_LAS bf16x8*)(lds + PG8_SB(b, h) + boff + n * 2048 + k * 1024); } while (0)
; template <class Epi, class Sched, bool ALIGN_EPI = false, bool SP2 = false>
; __device__ __forceinline__ void gemm_phase(PG8_LAS unsigned char* lds, const Gemm g, const Sched& S, const Epi& E) {
;     ...
;         const bool has_next = S.next(ui + 1, nxt);
;         const char* nA = has_next ? (const char*)g.A + (size_t)nxt.pm * tstep : cA; const char* nB = has_next ? (const char*)g.Bt + (size_t)nxt.pn * tstep : cB;
;         for (int t = 0; t < nt; t += 2) {
;             const bool last = (t == nt - 2);
;             const char* a1 = cA + (size_t)(t + 1) * kstep;
;             const char* a2 = last ? nA : cA + (size_t)(t + 2) * kstep; const char* b2 = last ? nB : cB + (size_t)(t + 2) * kstep;
;             const char* a3 = a2 + kstep; const char* b3 = b2 + kstep;
;             if (last && has_next) S.a_ready(nxt);
;             if constexpr (SP2) {
;             PG8_LDB(B0, 0, 0); PG8_LDB(B1, 0, 1); PG8_SCHED; PG8_LDA(At, 0, 0); PG8_STAGE(PG8_SA(1, 1), a1 + hstep, voffA);
;             PG8_WAIT_V(8); PG8_WAIT_L(0); PG8_BAR; PG8_MMA(0, 0, At, B0); PG8_MMA(0, 1, At, B1); PG8_BAR; PG8_SCHED;
;             PG8_LDA(At, 0, 1); PG8_STAGE(PG8_SB(0, 0), b2, voffB); PG8_STAGE(PG8_SB(0, 1), b2 + hstep, voffB); PG8_STAGE(PG8_SA(0, 0), a2, voffA);
;             PG8_WAIT_V(8); PG8_WAIT_L(0); PG8_BAR; PG8_MMA(1, 0, At, B0); PG8_MMA(1, 1, At, B1); PG8_BAR; PG8_SCHED;
;     __device__ __forceinline__ void operator()(const f32x4 (&acc)[2][2][4][2], const pg8::Unit& u, int wr, int wc, int fr, int fq) const {
;     ...
;         for (int ai = 0; ai < 2; ++ai)
; #pragma unroll
;             for (int m = 0; m < 4; ++m) rs8[ai][m] = rstd[256 * pm + 128 * ai + 64 * wr + 16 * m + fr];
.LBB0_410:
	s_lshl_b32 s98, s8, 8
	s_add_i32 s98, s98, s66
	v_add_lshl_u32 v255, v1, s98, 2
	global_load_dword v247, v255, s[16:17]
	global_load_dword v248, v255, s[16:17] offset:64
	global_load_dword v249, v255, s[16:17] offset:128
	global_load_dword v250, v255, s[16:17] offset:192
	global_load_dword v251, v255, s[16:17] offset:512
	global_load_dword v252, v255, s[16:17] offset:576
	global_load_dword v253, v255, s[16:17] offset:640
	global_load_dword v254, v255, s[16:17] offset:704
	s_ashr_i32 s35, s34, 31
	s_lshl_b64 s[0:1], s[34:35], 19
	s_add_u32 s38, s29, s0
	s_addc_u32 s39, s31, s1
	s_and_b64 s[0:1], s[10:11], exec
	s_cselect_b32 s0, s39, s5
	s_cselect_b32 s1, s38, s4
	s_ashr_i32 s37, s36, 31
	s_lshl_b64 s[40:41], s[36:37], 19
	s_add_u32 s40, s48, s40
	s_addc_u32 s41, s49, s41
	s_and_b64 s[44:45], s[10:11], exec
	s_cselect_b32 s9, s41, s7
	s_cselect_b32 s12, s40, s6
	s_add_u32 s4, s4, 0x40080
	s_addc_u32 s5, s5, 0
	s_add_u32 s33, s6, 0x100
	s_addc_u32 s35, s7, 0
	s_mov_b32 s37, -2
	ds_read_b128 v[130:133], v218
	ds_read_b128 v[134:137], v218 offset:1024
	ds_read_b128 v[138:141], v218 offset:2048
	ds_read_b128 v[142:145], v218 offset:3072
	ds_read_b128 v[146:149], v219
	ds_read_b128 v[150:153], v219 offset:1024
	ds_read_b128 v[154:157], v219 offset:2048
	ds_read_b128 v[158:161], v219 offset:3072
	s_add_u32 s6, s4, 0xfffc0080
	s_addc_u32 s7, s5, -1
	s_cmp_eq_u32 s37, 12
	s_cselect_b32 s45, s0, s7
	s_cselect_b32 s44, s1, s6
	s_cselect_b32 s7, s9, s35
	s_cselect_b32 s6, s12, s33
	v_lshl_add_u64 v[226:227], s[4:5], 0, v[188:189]
	s_add_i32 m0, s51, 0xc000
	s_waitcnt vmcnt(0)
	ds_read_b128 v[162:165], v220
	ds_read_b128 v[166:169], v220 offset:1024
	ds_read_b128 v[170:173], v220 offset:2048
	ds_read_b128 v[196:199], v220 offset:3072
	ds_read_b128 v[200:203], v220 offset:4096
	ds_read_b128 v[204:207], v220 offset:5120
	ds_read_b128 v[208:211], v220 offset:6144
	ds_read_b128 v[212:215], v220 offset:7168
	global_load_lds_dwordx4 v[226:227], off
	v_lshl_add_u64 v[226:227], s[4:5], 0, v[190:191]
	s_add_i32 m0, s51, 0xe000
	s_nop 0
	global_load_lds_dwordx4 v[226:227], off
	s_waitcnt vmcnt(8)
	s_waitcnt lgkmcnt(0)
	s_barrier
	s_setprio 1
	s_waitcnt lgkmcnt(0)
	v_mfma_f32_16x16x32_bf16 v[126:129], v[130:133], v[162:165], 0
	v_mfma_f32_16x16x32_bf16 v[122:125], v[138:141], v[162:165], 0
	v_mfma_f32_16x16x32_bf16 v[110:113], v[130:133], v[170:173], 0
	v_mfma_f32_16x16x32_bf16 v[106:109], v[138:141], v[170:173], 0
	v_mfma_f32_16x16x32_bf16 v[94:97], v[130:133], v[200:203], 0
	v_mfma_f32_16x16x32_bf16 v[90:93], v[138:141], v[200:203], 0
	v_mfma_f32_16x16x32_bf16 v[78:81], v[130:133], v[208:211], 0
	v_mfma_f32_16x16x32_bf16 v[74:77], v[138:141], v[208:211], 0
	v_mfma_f32_16x16x32_bf16 v[126:129], v[134:137], v[166:169], v[126:129]
	v_mfma_f32_16x16x32_bf16 v[122:125], v[142:145], v[166:169], v[122:125]
	v_mfma_f32_16x16x32_bf16 v[110:113], v[134:137], v[196:199], v[110:113]
	v_mfma_f32_16x16x32_bf16 v[106:109], v[142:145], v[196:199], v[106:109]
	v_mfma_f32_16x16x32_bf16 v[94:97], v[134:137], v[204:207], v[94:97]
	v_mfma_f32_16x16x32_bf16 v[90:93], v[142:145], v[204:207], v[90:93]
	v_mfma_f32_16x16x32_bf16 v[78:81], v[134:137], v[212:215], v[78:81]
	v_mfma_f32_16x16x32_bf16 v[74:77], v[142:145], v[212:215], v[74:77]
	s_setprio 0
	s_setprio 1
	v_mfma_f32_16x16x32_bf16 v[118:121], v[146:149], v[162:165], 0
	v_mfma_f32_16x16x32_bf16 v[114:117], v[154:157], v[162:165], 0
	v_mfma_f32_16x16x32_bf16 v[102:105], v[146:149], v[170:173], 0
	v_mfma_f32_16x16x32_bf16 v[98:101], v[154:157], v[170:173], 0
	v_mfma_f32_16x16x32_bf16 v[86:89], v[146:149], v[200:203], 0
	v_mfma_f32_16x16x32_bf16 v[82:85], v[154:157], v[200:203], 0
	v_mfma_f32_16x16x32_bf16 v[70:73], v[146:149], v[208:211], 0
	v_mfma_f32_16x16x32_bf16 v[66:69], v[154:157], v[208:211], 0
	v_mfma_f32_16x16x32_bf16 v[118:121], v[150:153], v[166:169], v[118:121]
	v_mfma_f32_16x16x32_bf16 v[114:117], v[158:161], v[166:169], v[114:117]
	v_mfma_f32_16x16x32_bf16 v[102:105], v[150:153], v[196:199], v[102:105]
	v_mfma_f32_16x16x32_bf16 v[98:101], v[158:161], v[196:199], v[98:101]
	v_mfma_f32_16x16x32_bf16 v[86:89], v[150:153], v[204:207], v[86:89]
	v_mfma_f32_16x16x32_bf16 v[82:85], v[158:161], v[204:207], v[82:85]
	v_mfma_f32_16x16x32_bf16 v[70:73], v[150:153], v[212:215], v[70:73]
	v_mfma_f32_16x16x32_bf16 v[66:69], v[158:161], v[212:215], v[66:69]
	s_setprio 0
	s_barrier
	s_add_i32 s43, s86, s50
	v_lshl_add_u64 v[226:227], s[6:7], 0, v[178:179]
	s_mov_b32 m0, s43
	ds_read_b128 v[162:165], v220 offset:16384
	ds_read_b128 v[166:169], v220 offset:17408
	ds_read_b128 v[170:173], v220 offset:18432
	ds_read_b128 v[196:199], v220 offset:19456
	ds_read_b128 v[200:203], v220 offset:20480
	ds_read_b128 v[204:207], v220 offset:21504
	ds_read_b128 v[208:211], v220 offset:22528
	ds_read_b128 v[212:215], v220 offset:23552
	global_load_lds_dwordx4 v[226:227], off
	s_add_i32 m0, s43, 0x2000
	s_add_u32 s46, s6, 0x40000
	v_lshl_add_u64 v[228:229], s[6:7], 0, v[182:183]
	s_addc_u32 s47, s7, 0
	s_add_i32 s43, s87, s50
	global_load_lds_dwordx4 v[228:229], off
	v_lshl_add_u64 v[230:231], s[46:47], 0, v[178:179]
	s_mov_b32 m0, s43
	v_lshl_add_u64 v[232:233], s[44:45], 0, v[180:181]
	global_load_lds_dwordx4 v[230:231], off
	v_lshl_add_u64 v[230:231], s[46:47], 0, v[182:183]
	s_add_i32 m0, s43, 0x2000
	s_nop 0
	global_load_lds_dwordx4 v[230:231], off
	v_lshl_add_u64 v[230:231], s[44:45], 0, v[176:177]
	s_mov_b32 m0, s51
	s_nop 0
	global_load_lds_dwordx4 v[230:231], off
	s_mov_b32 m0, s52
	s_nop 0
	global_load_lds_dwordx4 v[232:233], off
	s_waitcnt vmcnt(8)
	s_waitcnt lgkmcnt(0)
	s_barrier
; #define PG8_STAGE(bufoff, gbase, voff) do { _Pragma("unroll") for (int _i = 0; _i < 2; ++_i) \
;         __builtin_amdgcn_global_load_lds((const unsigned*)((const char*)(gbase) + (voff)[_i]), (PG8_LAS unsigned*)(lds + (bufoff) + ldsw + _i * 8192), 16, 0, 0); } while (0)
; #define PG8_LDA(dst, b, h) do { _Pragma("unroll") for (int m = 0; m < 4; ++m) _Pragma("unroll") for (int k = 0; k < 2; ++k) dst[m][k] = *(const PG8_LAS bf16x8*)(lds + PG8_SA(b, h) + aoff + m * 2048 + k * 1024); } while (0)
; #define PG8_LDB(dst, b, h) do { _Pragma("unroll") for (int n = 0; n < 2; ++n) _Pragma("unroll") for (int k = 0; k < 2; ++k) dst[n][k] = *(const PG8_LAS bf16x8*)(lds + PG8_SB(b, h) + boff + n * 2048 + k * 1024); } while (0)
; #define PG8_MMA(ai, bj, At, Bt) do { __builtin_amdgcn_s_setprio(1); _Pragma("unroll") for (int m = 0; m < 4; ++m) _Pragma("unroll") for (int n = 0; n < 2; ++n) _Pragma("unroll") for (int k = 0; k < 2; ++k) \
;         acc[ai][bj][m][n] = __builtin_amdgcn_mfma_f32_16x16x32_bf16(Bt[n][k], At[m][k], acc[ai][bj][m][n], 0, 0, 0); __builtin_amdgcn_s_setprio(0); } while (0)
; #define PG8_WAIT_V(n) asm volatile("s_waitcnt vmcnt(" #n ")" ::: "memory")
; #define PG8_WAIT_L(n) asm volatile("s_waitcnt lgkmcnt(" #n ")" ::: "memory")
; #define PG8_BAR __builtin_amdgcn_s_barrier()
; #define PG8_SCHED __builtin_amdgcn_sched_barrier(0)
; template <class Epi, class Sched, bool ALIGN_EPI = false, bool SP2 = false>
; __device__ __forceinline__ void gemm_phase(PG8_LAS unsigned char* lds, const Gemm g, const Sched& S, const Epi& E) {
;     ...
;             PG8_WAIT_V(8); PG8_WAIT_L(0); PG8_BAR; PG8_MMA(1, 0, At, B0); PG8_MMA(1, 1, At, B1); PG8_BAR; PG8_SCHED;
;             PG8_LDB(B0, 1, 0); PG8_LDB(B1, 1, 1); PG8_SCHED; PG8_LDA(At, 1, 0); PG8_STAGE(PG8_SA(0, 1), a2 + hstep, voffA);
;             PG8_WAIT_V(8); PG8_WAIT_L(0); PG8_BAR; PG8_MMA(0, 0, At, B0); PG8_MMA(0, 1, At, B1); PG8_BAR; PG8_SCHED;
	s_setprio 1
	s_waitcnt lgkmcnt(0)
	v_mfma_f32_16x16x32_bf16 v[62:65], v[130:133], v[162:165], 0
	v_mfma_f32_16x16x32_bf16 v[58:61], v[138:141], v[162:165], 0
	v_mfma_f32_16x16x32_bf16 v[46:49], v[130:133], v[170:173], 0
	v_mfma_f32_16x16x32_bf16 v[42:45], v[138:141], v[170:173], 0
	v_mfma_f32_16x16x32_bf16 v[30:33], v[130:133], v[200:203], 0
	v_mfma_f32_16x16x32_bf16 v[26:29], v[138:141], v[200:203], 0
	v_mfma_f32_16x16x32_bf16 v[14:17], v[130:133], v[208:211], 0
	v_mfma_f32_16x16x32_bf16 v[10:13], v[138:141], v[208:211], 0
	v_mfma_f32_16x16x32_bf16 v[62:65], v[134:137], v[166:169], v[62:65]
	v_mfma_f32_16x16x32_bf16 v[58:61], v[142:145], v[166:169], v[58:61]
	v_mfma_f32_16x16x32_bf16 v[46:49], v[134:137], v[196:199], v[46:49]
	v_mfma_f32_16x16x32_bf16 v[42:45], v[142:145], v[196:199], v[42:45]
	v_mfma_f32_16x16x32_bf16 v[30:33], v[134:137], v[204:207], v[30:33]
	v_mfma_f32_16x16x32_bf16 v[26:29], v[142:145], v[204:207], v[26:29]
	v_mfma_f32_16x16x32_bf16 v[14:17], v[134:137], v[212:215], v[14:17]
	v_mfma_f32_16x16x32_bf16 v[10:13], v[142:145], v[212:215], v[10:13]
	s_setprio 0
	s_setprio 1
	v_mfma_f32_16x16x32_bf16 v[54:57], v[146:149], v[162:165], 0
	v_mfma_f32_16x16x32_bf16 v[50:53], v[154:157], v[162:165], 0
	v_mfma_f32_16x16x32_bf16 v[38:41], v[146:149], v[170:173], 0
	v_mfma_f32_16x16x32_bf16 v[34:37], v[154:157], v[170:173], 0
	v_mfma_f32_16x16x32_bf16 v[22:25], v[146:149], v[200:203], 0
	v_mfma_f32_16x16x32_bf16 v[18:21], v[154:157], v[200:203], 0
	v_mfma_f32_16x16x32_bf16 v[6:9], v[146:149], v[208:211], 0
	v_mfma_f32_16x16x32_bf16 v[2:5], v[154:157], v[208:211], 0
	v_mfma_f32_16x16x32_bf16 v[54:57], v[150:153], v[166:169], v[54:57]
	v_mfma_f32_16x16x32_bf16 v[50:53], v[158:161], v[166:169], v[50:53]
	v_mfma_f32_16x16x32_bf16 v[38:41], v[150:153], v[196:199], v[38:41]
	v_mfma_f32_16x16x32_bf16 v[34:37], v[158:161], v[196:199], v[34:37]
	v_mfma_f32_16x16x32_bf16 v[22:25], v[150:153], v[204:207], v[22:25]
	v_mfma_f32_16x16x32_bf16 v[18:21], v[158:161], v[204:207], v[18:21]
	v_mfma_f32_16x16x32_bf16 v[6:9], v[150:153], v[212:215], v[6:9]
	v_mfma_f32_16x16x32_bf16 v[2:5], v[158:161], v[212:215], v[2:5]
	s_setprio 0
	s_barrier
	s_add_i32 s43, 0, 0x18000
	s_add_i32 s46, 0, 0x1c000
	v_add_u32_e32 v142, s43, v217
	v_add_u32_e32 v158, s46, v217
	ds_read_b128 v[130:133], v142
	ds_read_b128 v[134:137], v142 offset:1024
	ds_read_b128 v[138:141], v142 offset:2048
	ds_read_b128 v[142:145], v142 offset:3072
	ds_read_b128 v[146:149], v158
	ds_read_b128 v[150:153], v158 offset:1024
	ds_read_b128 v[154:157], v158 offset:2048
	ds_read_b128 v[158:161], v158 offset:3072
	s_add_u32 s44, s44, 0x40000
	s_addc_u32 s45, s45, 0
	s_mov_b32 m0, s53
	v_lshl_add_u64 v[234:235], s[44:45], 0, v[176:177]
	ds_read_b128 v[162:165], v220 offset:32768
	ds_read_b128 v[166:169], v220 offset:33792
	ds_read_b128 v[170:173], v220 offset:34816
	ds_read_b128 v[196:199], v220 offset:35840
	ds_read_b128 v[200:203], v220 offset:36864
	ds_read_b128 v[204:207], v220 offset:37888
	ds_read_b128 v[208:211], v220 offset:38912
	ds_read_b128 v[212:215], v220 offset:39936
	global_load_lds_dwordx4 v[234:235], off
	v_lshl_add_u64 v[234:235], s[44:45], 0, v[180:181]
	s_mov_b32 m0, s54
	s_nop 0
	global_load_lds_dwordx4 v[234:235], off
	s_waitcnt vmcnt(8)
	s_waitcnt lgkmcnt(0)
	s_barrier
	s_setprio 1
	s_waitcnt lgkmcnt(0)
	v_mfma_f32_16x16x32_bf16 v[126:129], v[130:133], v[162:165], v[126:129]
	v_mfma_f32_16x16x32_bf16 v[122:125], v[138:141], v[162:165], v[122:125]
	v_mfma_f32_16x16x32_bf16 v[110:113], v[130:133], v[170:173], v[110:113]
	v_mfma_f32_16x16x32_bf16 v[106:109], v[138:141], v[170:173], v[106:109]
	v_mfma_f32_16x16x32_bf16 v[94:97], v[130:133], v[200:203], v[94:97]
	v_mfma_f32_16x16x32_bf16 v[90:93], v[138:141], v[200:203], v[90:93]
	v_mfma_f32_16x16x32_bf16 v[78:81], v[130:133], v[208:211], v[78:81]
	v_mfma_f32_16x16x32_bf16 v[74:77], v[138:141], v[208:211], v[74:77]
	v_mfma_f32_16x16x32_bf16 v[126:129], v[134:137], v[166:169], v[126:129]
	v_mfma_f32_16x16x32_bf16 v[122:125], v[142:145], v[166:169], v[122:125]
	v_mfma_f32_16x16x32_bf16 v[110:113], v[134:137], v[196:199], v[110:113]
	v_mfma_f32_16x16x32_bf16 v[106:109], v[142:145], v[196:199], v[106:109]
	v_mfma_f32_16x16x32_bf16 v[94:97], v[134:137], v[204:207], v[94:97]
	v_mfma_f32_16x16x32_bf16 v[90:93], v[142:145], v[204:207], v[90:93]
	v_mfma_f32_16x16x32_bf16 v[78:81], v[134:137], v[212:215], v[78:81]
	v_mfma_f32_16x16x32_bf16 v[74:77], v[142:145], v[212:215], v[74:77]
	s_setprio 0
	s_setprio 1
	v_mfma_f32_16x16x32_bf16 v[118:121], v[146:149], v[162:165], v[118:121]
	v_mfma_f32_16x16x32_bf16 v[114:117], v[154:157], v[162:165], v[114:117]
	v_mfma_f32_16x16x32_bf16 v[102:105], v[146:149], v[170:173], v[102:105]
	v_mfma_f32_16x16x32_bf16 v[98:101], v[154:157], v[170:173], v[98:101]
	v_mfma_f32_16x16x32_bf16 v[86:89], v[146:149], v[200:203], v[86:89]
	v_mfma_f32_16x16x32_bf16 v[82:85], v[154:157], v[200:203], v[82:85]
	v_mfma_f32_16x16x32_bf16 v[70:73], v[146:149], v[208:211], v[70:73]
	v_mfma_f32_16x16x32_bf16 v[66:69], v[154:157], v[208:211], v[66:69]
	v_mfma_f32_16x16x32_bf16 v[118:121], v[150:153], v[166:169], v[118:121]
	v_mfma_f32_16x16x32_bf16 v[114:117], v[158:161], v[166:169], v[114:117]
	v_mfma_f32_16x16x32_bf16 v[102:105], v[150:153], v[196:199], v[102:105]
	v_mfma_f32_16x16x32_bf16 v[98:101], v[158:161], v[196:199], v[98:101]
	v_mfma_f32_16x16x32_bf16 v[86:89], v[150:153], v[204:207], v[86:89]
	v_mfma_f32_16x16x32_bf16 v[82:85], v[158:161], v[204:207], v[82:85]
	v_mfma_f32_16x16x32_bf16 v[70:73], v[150:153], v[212:215], v[70:73]
	v_mfma_f32_16x16x32_bf16 v[66:69], v[158:161], v[212:215], v[66:69]
	s_setprio 0
	s_barrier
; #define PG8_STAGE(bufoff, gbase, voff) do { _Pragma("unroll") for (int _i = 0; _i < 2; ++_i) \
;         __builtin_amdgcn_global_load_lds((const unsigned*)((const char*)(gbase) + (voff)[_i]), (PG8_LAS unsigned*)(lds + (bufoff) + ldsw + _i * 8192), 16, 0, 0); } while (0)
; #define PG8_LDA(dst, b, h) do { _Pragma("unroll") for (int m = 0; m < 4; ++m) _Pragma("unroll") for (int k = 0; k < 2; ++k) dst[m][k] = *(const PG8_LAS bf16x8*)(lds + PG8_SA(b, h) + aoff + m * 2048 + k * 1024); } while (0)
; #define PG8_MMA(ai, bj, At, Bt) do { __builtin_amdgcn_s_setprio(1); _Pragma("unroll") for (int m = 0; m < 4; ++m) _Pragma("unroll") for (int n = 0; n < 2; ++n) _Pragma("unroll") for (int k = 0; k < 2; ++k) \
;         acc[ai][bj][m][n] = __builtin_amdgcn_mfma_f32_16x16x32_bf16(Bt[n][k], At[m][k], acc[ai][bj][m][n], 0, 0, 0); __builtin_amdgcn_s_setprio(0); } while (0)
; #define PG8_WAIT_V(n) asm volatile("s_waitcnt vmcnt(" #n ")" ::: "memory")
; #define PG8_WAIT_L(n) asm volatile("s_waitcnt lgkmcnt(" #n ")" ::: "memory")
; #define PG8_BAR __builtin_amdgcn_s_barrier()
; #define PG8_SCHED __builtin_amdgcn_sched_barrier(0)
; template <class Epi, class Sched, bool ALIGN_EPI = false, bool SP2 = false>
; __device__ __forceinline__ void gemm_phase(PG8_LAS unsigned char* lds, const Gemm g, const Sched& S, const Epi& E) {
;     ...
;         for (int t = 0; t < nt; t += 2) {
;             const bool last = (t == nt - 2);
;             const char* a1 = cA + (size_t)(t + 1) * kstep;
;             const char* a2 = last ? nA : cA + (size_t)(t + 2) * kstep; const char* b2 = last ? nB : cB + (size_t)(t + 2) * kstep;
;     ...
;             PG8_LDA(At, 1, 1); PG8_STAGE(PG8_SB(1, 0), b3, voffB); PG8_STAGE(PG8_SB(1, 1), b3 + hstep, voffB); PG8_STAGE(PG8_SA(1, 0), a3, voffA);
;             PG8_WAIT_V(8); PG8_WAIT_L(0); PG8_BAR; PG8_MMA(1, 0, At, B0); PG8_MMA(1, 1, At, B1); PG8_BAR; PG8_SCHED;
	s_add_i32 s43, s43, s50
	v_lshl_add_u64 v[226:227], v[226:227], 0, s[20:21]
	s_mov_b32 m0, s43
	ds_read_b128 v[162:165], v220 offset:49152
	ds_read_b128 v[166:169], v220 offset:50176
	ds_read_b128 v[170:173], v220 offset:51200
	ds_read_b128 v[196:199], v220 offset:52224
	ds_read_b128 v[200:203], v220 offset:53248
	ds_read_b128 v[204:207], v220 offset:54272
	ds_read_b128 v[208:211], v220 offset:55296
	ds_read_b128 v[212:215], v220 offset:56320
	global_load_lds_dwordx4 v[226:227], off
	s_add_i32 m0, s43, 0x2000
	s_add_u32 s6, s6, 0x40080
	v_lshl_add_u64 v[226:227], v[228:229], 0, s[20:21]
	s_addc_u32 s7, s7, 0
	s_add_i32 s43, s46, s50
	global_load_lds_dwordx4 v[226:227], off
	v_lshl_add_u64 v[226:227], s[6:7], 0, v[178:179]
	s_mov_b32 m0, s43
	s_nop 0
	global_load_lds_dwordx4 v[226:227], off
	v_lshl_add_u64 v[226:227], s[6:7], 0, v[182:183]
	s_add_i32 m0, s43, 0x2000
	s_nop 0
	global_load_lds_dwordx4 v[226:227], off
	v_lshl_add_u64 v[226:227], v[230:231], 0, s[20:21]
	s_mov_b32 m0, s67
	s_nop 0
	global_load_lds_dwordx4 v[226:227], off
	v_lshl_add_u64 v[226:227], v[232:233], 0, s[20:21]
	s_mov_b32 m0, s68
	s_nop 0
	global_load_lds_dwordx4 v[226:227], off
	s_waitcnt vmcnt(8)
	s_waitcnt lgkmcnt(0)
	s_barrier
	s_setprio 1
	s_waitcnt lgkmcnt(0)
	v_mfma_f32_16x16x32_bf16 v[62:65], v[130:133], v[162:165], v[62:65]
	v_mfma_f32_16x16x32_bf16 v[58:61], v[138:141], v[162:165], v[58:61]
	v_mfma_f32_16x16x32_bf16 v[46:49], v[130:133], v[170:173], v[46:49]
	v_mfma_f32_16x16x32_bf16 v[42:45], v[138:141], v[170:173], v[42:45]
	v_mfma_f32_16x16x32_bf16 v[30:33], v[130:133], v[200:203], v[30:33]
	v_mfma_f32_16x16x32_bf16 v[26:29], v[138:141], v[200:203], v[26:29]
	v_mfma_f32_16x16x32_bf16 v[14:17], v[130:133], v[208:211], v[14:17]
	v_mfma_f32_16x16x32_bf16 v[10:13], v[138:141], v[208:211], v[10:13]
	v_mfma_f32_16x16x32_bf16 v[62:65], v[134:137], v[166:169], v[62:65]
	v_mfma_f32_16x16x32_bf16 v[58:61], v[142:145], v[166:169], v[58:61]
	v_mfma_f32_16x16x32_bf16 v[46:49], v[134:137], v[196:199], v[46:49]
	v_mfma_f32_16x16x32_bf16 v[42:45], v[142:145], v[196:199], v[42:45]
	v_mfma_f32_16x16x32_bf16 v[30:33], v[134:137], v[204:207], v[30:33]
	v_mfma_f32_16x16x32_bf16 v[26:29], v[142:145], v[204:207], v[26:29]
	v_mfma_f32_16x16x32_bf16 v[14:17], v[134:137], v[212:215], v[14:17]
	v_mfma_f32_16x16x32_bf16 v[10:13], v[142:145], v[212:215], v[10:13]
	s_setprio 0
	s_setprio 1
	v_mfma_f32_16x16x32_bf16 v[54:57], v[146:149], v[162:165], v[54:57]
	v_mfma_f32_16x16x32_bf16 v[50:53], v[154:157], v[162:165], v[50:53]
	v_mfma_f32_16x16x32_bf16 v[38:41], v[146:149], v[170:173], v[38:41]
	v_mfma_f32_16x16x32_bf16 v[34:37], v[154:157], v[170:173], v[34:37]
	v_mfma_f32_16x16x32_bf16 v[22:25], v[146:149], v[200:203], v[22:25]
	v_mfma_f32_16x16x32_bf16 v[18:21], v[154:157], v[200:203], v[18:21]
	v_mfma_f32_16x16x32_bf16 v[6:9], v[146:149], v[208:211], v[6:9]
	v_mfma_f32_16x16x32_bf16 v[2:5], v[154:157], v[208:211], v[2:5]
	v_mfma_f32_16x16x32_bf16 v[54:57], v[150:153], v[166:169], v[54:57]
	v_mfma_f32_16x16x32_bf16 v[50:53], v[158:161], v[166:169], v[50:53]
	v_mfma_f32_16x16x32_bf16 v[38:41], v[150:153], v[196:199], v[38:41]
	v_mfma_f32_16x16x32_bf16 v[34:37], v[158:161], v[196:199], v[34:37]
	v_mfma_f32_16x16x32_bf16 v[22:25], v[150:153], v[204:207], v[22:25]
	v_mfma_f32_16x16x32_bf16 v[18:21], v[158:161], v[204:207], v[18:21]
	v_mfma_f32_16x16x32_bf16 v[6:9], v[150:153], v[212:215], v[6:9]
	v_mfma_f32_16x16x32_bf16 v[2:5], v[158:161], v[212:215], v[2:5]
	s_setprio 0
	s_barrier
	s_add_i32 s37, s37, 2
	s_add_u32 s4, s4, 0x100
	s_addc_u32 s5, s5, 0
	s_add_u32 s33, s33, 0x100
	s_addc_u32 s35, s35, 0
	s_cmp_gt_u32 s37, 13
